# selected-branch K/V gathered with 16-byte loads (in-place fragment re-layout pass in phase 2) + hand-scheduled window/cmp loops
# speedup vs baseline: 1.0691x; 1.0507x over previous
; __device__ __forceinline__ CArgs* get_args() { CArgs* p = (CArgs*)__builtin_amdgcn_kernarg_segment_ptr(); asm volatile("" : "+s"(p)); return p; }
; __device__ __forceinline__ void load_kh8(long (&kf)[2][2], const unsigned char* Kb, int hh, int lane) {
; #pragma unroll
;     for (int nt = 0; nt < 2; ++nt)
; #pragma unroll
;         for (int kk = 0; kk < 2; ++kk) kf[nt][kk] = *(const long*)(Kb + (((2 * hh + nt) * 2 + kk) * 64 + lane) * 8);
; }
; __device__ __forceinline__ void load_vh8(long (&vf)[4], const unsigned char* Vb, int hh, int lane) {
; #pragma unroll
;     for (int dt = 0; dt < 4; ++dt) vf[dt] = *(const long*)(Vb + ((dt * 2 + hh) * 64 + lane) * 8);
; }
; __global__ void __launch_bounds__(512, 2) hymba_fwd(Args A_unused) {
;     ...
;         {
;             PHASE_IDS(); CArgs* Ap = get_args();
;             for (int wt = blk; wt < 256; wt += G) { const int b_ = wt >> 7, cp_ = (wt >> 4) & 7, gq_ = wt & 15;
;                 s5_task<2>(Ap, l, b_, 4 * gq_ + (wave & 3), 2 * cp_ + (wave >> 2), lds + wave * 8192, lane); }
.LBB0_812:
	s_or_b64 exec, exec, s[0:1]
	s_mov_b32 s0, s77
	s_barrier
	buffer_inv sc1
	s_waitcnt vmcnt(0) lgkmcnt(0)
	v_mbcnt_lo_u32_b32 v0, -1, 0
	v_mbcnt_hi_u32_b32 v0, -1, v0
	s_mov_b32 s17, s67
	v_lshl_add_u32 v5, s0, 6, v0
	s_mov_b32 s18, s76
	v_readfirstlane_b32 s19, v5
	s_ashr_i32 s16, s19, 6
	v_and_b32_e32 v4, 63, v5
	s_mov_b64 s[0:1], s[68:69]
	s_load_dwordx2 s[2:3], s[0:1], 0xd8
	s_lshl_b32 s4, s18, 3
	s_add_i32 s4, s4, s16
	s_cmp_lt_u32 s4, 0x400
	s_mov_b32 s5, 0x29200000
	s_cselect_b32 s5, 0x2c000000, s5
	s_cselect_b64 s[6:7], -1, 0
	s_and_b32 s4, s4, 0x3ff
	s_lshl_b32 s4, s4, 12
	v_lshlrev_b32_e32 v228, 3, v4
	v_lshlrev_b32_e32 v229, 4, v4
	s_waitcnt lgkmcnt(0)
	s_add_u32 s2, s2, s5
	s_addc_u32 s3, s3, 0
	s_add_u32 s2, s2, s4
	s_addc_u32 s3, s3, 0
	s_and_b64 vcc, exec, s[6:7]
	s_cbranch_vccz .Lrel_v
	global_load_dwordx2 v[230:231], v228, s[2:3] offset:0
	global_load_dwordx2 v[232:233], v228, s[2:3] offset:512
	global_load_dwordx2 v[234:235], v228, s[2:3] offset:1024
	global_load_dwordx2 v[236:237], v228, s[2:3] offset:1536
	global_load_dwordx2 v[238:239], v228, s[2:3] offset:2048
	global_load_dwordx2 v[240:241], v228, s[2:3] offset:2560
	global_load_dwordx2 v[242:243], v228, s[2:3] offset:3072
	global_load_dwordx2 v[244:245], v228, s[2:3] offset:3584
	s_branch .Lrel_st
.Lrel_v:
	global_load_dwordx2 v[230:231], v228, s[2:3] offset:0
	global_load_dwordx2 v[238:239], v228, s[2:3] offset:512
	global_load_dwordx2 v[232:233], v228, s[2:3] offset:1024
	global_load_dwordx2 v[240:241], v228, s[2:3] offset:1536
	global_load_dwordx2 v[234:235], v228, s[2:3] offset:2048
	global_load_dwordx2 v[242:243], v228, s[2:3] offset:2560
	global_load_dwordx2 v[236:237], v228, s[2:3] offset:3072
	global_load_dwordx2 v[244:245], v228, s[2:3] offset:3584
.Lrel_st:
	s_waitcnt vmcnt(0)
	global_store_dwordx4 v229, v[230:233], s[2:3] offset:0
	global_store_dwordx4 v229, v[234:237], s[2:3] offset:1024
	global_store_dwordx4 v229, v[238:241], s[2:3] offset:2048
	global_store_dwordx4 v229, v[242:245], s[2:3] offset:3072
	s_cmpk_gt_i32 s18, 0xff
	s_cbranch_scc1 .LBB0_830
	v_lshlrev_b32_e32 v0, 2, v4
	s_lshl_b32 s2, s16, 13
	v_lshrrev_b32_e32 v8, 2, v4
	v_and_b32_e32 v0, 12, v0
	s_add_i32 s12, s2, 0
	v_readlane_b32 s2, v254, 4
	v_lshlrev_b32_e32 v1, 6, v8
	v_lshlrev_b32_e32 v2, 2, v0
	s_bfe_u32 s10, s19, 0x20006
	s_ashr_i32 s11, s19, 8
	s_lshl_b32 s13, s2, 6
	v_lshlrev_b32_e32 v6, 4, v4
	v_add3_u32 v7, s12, v1, v2
	v_lshlrev_b32_e32 v10, 1, v0
	v_lshlrev_b32_e32 v12, 3, v4
	s_mov_b32 s14, s18
	v_readlane_b32 s3, v254, 5
	s_branch .LBB0_816

; __device__ __forceinline__ void nsa_wave(CArgs* Ap, int l, int b, int g, int tq0, const LAS float* lut, LAS float* imp, int lane) {
;     ...
;     {
;         SmState st{-1e30f, 0.f};
;         f32x4 Od[4];
; #pragma unroll
;         for (int dt = 0; dt < 4; ++dt) Od[dt] = (f32x4){0.f, 0.f, 0.f, 0.f};
;         bf16x8 pB[2];
;         for (int cb = 0; cb < ncb; ++cb) {
;             bf16x8 kf[4][2]; load_k(kf, KC + (size_t)cb * 4096, lane);
;             f32x4 acc[4];
; #pragma unroll
;             for (int nt = 0; nt < 4; ++nt) acc[nt] = (f32x4){0.f, 0.f, 0.f, 0.f};
;             qk_acc(acc, kf, qB);
.LBB0_895:
	s_lshl_b32 s20, s0, 2
	s_sub_i32 s0, s19, 28
	s_lshr_b32 s21, s0, 10
	v_lshl_add_u32 v206, s17, 14, v132
	s_andn2_b64 vcc, exec, s[46:47]
	v_add_u32_e32 v75, s18, v202
	s_cbranch_vccnz .LBB0_899
	s_add_i32 s0, s20, s17
	s_ashr_i32 s1, s0, 31
	s_add_i32 s72, s21, 1
	s_lshl_b64 s[0:1], s[0:1], 16
	s_add_u32 s0, s15, s0
	s_addc_u32 s1, s16, s1
	v_xor_b32_e32 v21, 16, v170
	v_xor_b32_e32 v22, 32, v170
	v_lshl_add_u64 v[102:103], s[0:1], 0, v[84:85]
	s_mov_b32 s23, 0x2a201000
	v_add_co_u32_e32 v100, vcc, s23, v102
	v_add_u32_e32 v122, s18, v202
	s_mov_b64 s[0:1], 0x2000
	v_addc_co_u32_e32 v101, vcc, 0, v103, vcc
	v_mov_b32_e32 v76, 0xf149f2ca
	v_mov_b32_e32 v8, 0
	global_load_dwordx4 v[24:27], v[100:101], off offset:-4096
	global_load_dwordx4 v[28:31], v[100:101], off offset:-3072
	global_load_dwordx4 v[32:35], v[100:101], off offset:-2048
	global_load_dwordx4 v[36:39], v[100:101], off offset:-1024
	global_load_dwordx4 v[40:43], v[100:101], off offset:0
	global_load_dwordx4 v[44:47], v[100:101], off offset:1024
	global_load_dwordx4 v[48:51], v[100:101], off offset:2048
	global_load_dwordx4 v[52:55], v[100:101], off offset:3072
.Lc1_loop:
	v_add_u32_e32 v244, 0x330, v122
	v_cmp_lt_i32_e64 s[46:47], -1, v244
	v_med3_i32 v244, v244, 0, v181
	v_lshl_add_u32 v244, v244, 4, v206
	ds_read_b32 v244, v244
	v_add_u32_e32 v245, 0x320, v122
	v_cmp_lt_i32_e64 s[48:49], -1, v245
	v_med3_i32 v245, v245, 0, v181
	v_lshl_add_u32 v245, v245, 4, v206
	ds_read_b32 v245, v245
	v_add_u32_e32 v246, 0x310, v122
	v_cmp_lt_i32_e64 s[50:51], -1, v246
	v_med3_i32 v246, v246, 0, v181
	v_lshl_add_u32 v246, v246, 4, v206
	ds_read_b32 v246, v246
	v_add_u32_e32 v247, 0x300, v122
	v_cmp_lt_i32_e64 s[52:53], -1, v247
	v_med3_i32 v247, v247, 0, v181
	v_lshl_add_u32 v247, v247, 4, v206
	ds_read_b32 v247, v247
	v_add_u32_e32 v248, 0x230, v122
	v_cmp_lt_i32_e64 s[54:55], -1, v248
	v_med3_i32 v248, v248, 0, v181
	v_lshl_add_u32 v248, v248, 4, v206
	ds_read_b32 v248, v248
	v_add_u32_e32 v249, 0x220, v122
	v_cmp_lt_i32_e64 s[56:57], -1, v249
	v_med3_i32 v249, v249, 0, v181
	v_lshl_add_u32 v249, v249, 4, v206
	ds_read_b32 v249, v249
	v_add_u32_e32 v250, 0x210, v122
	v_cmp_lt_i32_e64 s[58:59], -1, v250
	v_med3_i32 v250, v250, 0, v181
	v_lshl_add_u32 v250, v250, 4, v206
	ds_read_b32 v250, v250
	v_add_u32_e32 v251, 0x200, v122
	v_cmp_lt_i32_e64 s[60:61], -1, v251
	v_med3_i32 v251, v251, 0, v181
	v_lshl_add_u32 v251, v251, 4, v206
	ds_read_b32 v251, v251
	v_add_u32_e32 v252, 0x130, v122
	v_cmp_lt_i32_e64 s[62:63], -1, v252
	v_med3_i32 v252, v252, 0, v181
	v_lshl_add_u32 v252, v252, 4, v206
	ds_read_b32 v252, v252
	v_add_u32_e32 v253, 0x120, v122
	v_cmp_lt_i32_e64 s[64:65], -1, v253
	v_med3_i32 v253, v253, 0, v181
	v_lshl_add_u32 v253, v253, 4, v206
	ds_read_b32 v253, v253
	v_add_u32_e32 v255, 0x110, v122
	v_cmp_lt_i32_e64 s[66:67], -1, v255
	v_med3_i32 v255, v255, 0, v181
	v_lshl_add_u32 v255, v255, 4, v206
	ds_read_b32 v255, v255
	v_add_u32_e32 v98, 0x100, v122
	v_cmp_lt_i32_e64 s[68:69], -1, v98
	v_med3_i32 v98, v98, 0, v181
	v_lshl_add_u32 v98, v98, 4, v206
	ds_read_b32 v98, v98
	v_add_u32_e32 v99, 0x30, v122
	v_cmp_lt_i32_e64 s[24:25], -1, v99
	v_med3_i32 v99, v99, 0, v181
	v_lshl_add_u32 v99, v99, 4, v206
	ds_read_b32 v99, v99
	v_add_u32_e32 v116, 0x20, v122
	v_cmp_lt_i32_e64 s[98:99], -1, v116
	v_med3_i32 v116, v116, 0, v181
	v_lshl_add_u32 v116, v116, 4, v206
	ds_read_b32 v116, v116
	v_add_u32_e32 v117, 0x10, v122
	v_cmp_lt_i32_e64 s[100:101], -1, v117
	v_med3_i32 v117, v117, 0, v181
	v_lshl_add_u32 v117, v117, 4, v206
	ds_read_b32 v117, v117
	v_add_u32_e32 v118, 0x0, v122
	v_cmp_lt_i32_e64 s[22:23], -1, v118
	v_med3_i32 v118, v118, 0, v181
	v_lshl_add_u32 v118, v118, 4, v206
	ds_read_b32 v118, v118
	v_add_u32_e32 v122, 0xfffffc00, v122
	s_add_i32 s72, s72, -1
	s_waitcnt vmcnt(0)
	v_mfma_f32_16x16x32_bf16 v[228:231], v[24:27], v[0:3], 0
	v_mfma_f32_16x16x32_bf16 v[232:235], v[32:35], v[0:3], 0
	v_mfma_f32_16x16x32_bf16 v[236:239], v[40:43], v[0:3], 0
	v_mfma_f32_16x16x32_bf16 v[240:243], v[48:51], v[0:3], 0
	v_mfma_f32_16x16x32_bf16 v[228:231], v[28:31], v[4:7], v[228:231]
	v_mfma_f32_16x16x32_bf16 v[232:235], v[36:39], v[4:7], v[232:235]
	v_mfma_f32_16x16x32_bf16 v[236:239], v[44:47], v[4:7], v[236:239]
	v_mfma_f32_16x16x32_bf16 v[240:243], v[52:55], v[4:7], v[240:243]
	s_cmp_eq_u32 s72, 0
	s_cbranch_scc1 .Lc1_nokpf
	v_lshl_add_u64 v[100:101], v[100:101], 0, s[0:1]
	global_load_dwordx4 v[24:27], v[100:101], off offset:-4096
	global_load_dwordx4 v[28:31], v[100:101], off offset:-3072
	global_load_dwordx4 v[32:35], v[100:101], off offset:-2048
	global_load_dwordx4 v[36:39], v[100:101], off offset:-1024
	global_load_dwordx4 v[40:43], v[100:101], off offset:0
	global_load_dwordx4 v[44:47], v[100:101], off offset:1024
	global_load_dwordx4 v[48:51], v[100:101], off offset:2048
	global_load_dwordx4 v[52:55], v[100:101], off offset:3072
; #define LAS __attribute__((address_space(3)))
; __device__ __forceinline__ float fexp(float x) { return __expf(x); }
; template <int MODE>
; __device__ __forceinline__ void softmax_block(f32x4 (&acc)[4], int base, bool ok, int t, int g4, const LAS float* lutg, SmState& st, f32x4 (&O)[4], bf16x8 (&pB)[2]) {
;     float mx = -1e30f; unsigned vm = 0u;
; #pragma unroll
;     for (int nt = 0; nt < 4; ++nt)
; #pragma unroll
;         for (int i = 0; i < 4; ++i) {
;             const int key = base + 16 * nt + 4 * g4 + i;
;             const int dist = (MODE == 0) ? t - (16 * key + 31) : t - key;
;             bool valid = dist >= 0;
;             if (MODE == 1) valid = valid && ok;
;             if (MODE == 2) valid = valid && dist < 512;
;             int dc = dist < 0 ? 0 : dist; dc = dc > 1023 ? 1023 : dc;
;             const float lg = acc[nt][i] + lutg[dc * 4];
;             acc[nt][i] = lg;
;             if (valid) { mx = fmaxf(mx, lg); vm |= 1u << (nt * 4 + i); }
;         }
;     mx = fmaxf(mx, __shfl_xor(mx, 16)); mx = fmaxf(mx, __shfl_xor(mx, 32));
;     const float mn = fmaxf(st.m, mx);
;     const float sc = fexp(st.m - mn);
;     float ls = 0.f;
; #pragma unroll
;     for (int nt = 0; nt < 4; ++nt)
; #pragma unroll
;         for (int i = 0; i < 4; ++i) { const float p = ((vm >> (nt * 4 + i)) & 1u) ? fexp(acc[nt][i] - mn) : 0.f; acc[nt][i] = p; ls += p; }
;     st.l = st.l * sc + ls; st.m = mn;
.Lc1_nokpf:
	s_waitcnt lgkmcnt(0)
	s_nop 7
	v_add_f32_e32 v228, v228, v244
	v_add_f32_e32 v229, v229, v245
	v_add_f32_e32 v230, v230, v246
	v_add_f32_e32 v231, v231, v247
	v_add_f32_e32 v232, v232, v248
	v_add_f32_e32 v233, v233, v249
	v_add_f32_e32 v234, v234, v250
	v_add_f32_e32 v235, v235, v251
	v_add_f32_e32 v236, v236, v252
	v_add_f32_e32 v237, v237, v253
	v_add_f32_e32 v238, v238, v255
	v_add_f32_e32 v239, v239, v98
	v_add_f32_e32 v240, v240, v99
	v_add_f32_e32 v241, v241, v116
	v_add_f32_e32 v242, v242, v117
	v_add_f32_e32 v243, v243, v118
	v_cndmask_b32_e64 v244, v182, v228, s[46:47]
	v_cndmask_b32_e64 v245, v182, v229, s[48:49]
	v_cndmask_b32_e64 v246, v182, v230, s[50:51]
	v_cndmask_b32_e64 v247, v182, v231, s[52:53]
	v_cndmask_b32_e64 v248, v182, v232, s[54:55]
	v_cndmask_b32_e64 v249, v182, v233, s[56:57]
	v_cndmask_b32_e64 v250, v182, v234, s[58:59]
	v_cndmask_b32_e64 v251, v182, v235, s[60:61]
	v_cndmask_b32_e64 v252, v182, v236, s[62:63]
	v_cndmask_b32_e64 v253, v182, v237, s[64:65]
	v_cndmask_b32_e64 v255, v182, v238, s[66:67]
	v_cndmask_b32_e64 v98, v182, v239, s[68:69]
	v_cndmask_b32_e64 v99, v182, v240, s[24:25]
	v_cndmask_b32_e64 v116, v182, v241, s[98:99]
	v_cndmask_b32_e64 v117, v182, v242, s[100:101]
	v_cndmask_b32_e64 v118, v182, v243, s[22:23]
	v_max3_f32 v244, v244, v245, v246
	v_max3_f32 v247, v247, v248, v249
	v_max3_f32 v250, v250, v251, v252
	v_max3_f32 v253, v253, v255, v98
	v_max3_f32 v99, v99, v116, v117
	v_max3_f32 v244, v244, v247, v250
	v_max3_f32 v253, v253, v99, v118
	v_max_f32_e32 v244, v244, v253
	v_mov_b32_e32 v120, v244
	s_nop 1
	v_permlane16_swap_b32_e32 v244, v120
	v_max_f32_e32 v244, v244, v120
	v_mov_b32_e32 v120, v244
	s_nop 1
	v_permlane32_swap_b32_e32 v244, v120
	v_max3_f32 v124, v76, v244, v120
	v_sub_f32_e32 v126, v76, v124
	v_sub_f32_e32 v228, v228, v124
	v_sub_f32_e32 v229, v229, v124
	v_sub_f32_e32 v230, v230, v124
	v_sub_f32_e32 v231, v231, v124
	v_sub_f32_e32 v232, v232, v124
	v_sub_f32_e32 v233, v233, v124
	v_sub_f32_e32 v234, v234, v124
	v_sub_f32_e32 v235, v235, v124
	v_sub_f32_e32 v236, v236, v124
	v_sub_f32_e32 v237, v237, v124
	v_sub_f32_e32 v238, v238, v124
	v_sub_f32_e32 v239, v239, v124
	v_sub_f32_e32 v240, v240, v124
	v_sub_f32_e32 v241, v241, v124
	v_sub_f32_e32 v242, v242, v124
	v_sub_f32_e32 v243, v243, v124
	v_mul_f32_e32 v126, 0x3fb8aa3b, v126
	v_mul_f32_e32 v228, 0x3fb8aa3b, v228
	v_mul_f32_e32 v229, 0x3fb8aa3b, v229
	v_mul_f32_e32 v230, 0x3fb8aa3b, v230
	v_mul_f32_e32 v231, 0x3fb8aa3b, v231
	v_mul_f32_e32 v232, 0x3fb8aa3b, v232
	v_mul_f32_e32 v233, 0x3fb8aa3b, v233
	v_mul_f32_e32 v234, 0x3fb8aa3b, v234
	v_mul_f32_e32 v235, 0x3fb8aa3b, v235
	v_mul_f32_e32 v236, 0x3fb8aa3b, v236
	v_mul_f32_e32 v237, 0x3fb8aa3b, v237
	v_mul_f32_e32 v238, 0x3fb8aa3b, v238
	v_mul_f32_e32 v239, 0x3fb8aa3b, v239
	v_mul_f32_e32 v240, 0x3fb8aa3b, v240
	v_mul_f32_e32 v241, 0x3fb8aa3b, v241
	v_mul_f32_e32 v242, 0x3fb8aa3b, v242
	v_mul_f32_e32 v243, 0x3fb8aa3b, v243
	v_exp_f32_e32 v126, v126
	v_exp_f32_e32 v228, v228
	v_exp_f32_e32 v229, v229
	v_exp_f32_e32 v230, v230
	v_exp_f32_e32 v231, v231
	v_exp_f32_e32 v232, v232
	v_exp_f32_e32 v233, v233
	v_exp_f32_e32 v234, v234
	v_exp_f32_e32 v235, v235
	v_exp_f32_e32 v236, v236
	v_exp_f32_e32 v237, v237
	v_exp_f32_e32 v238, v238
	v_exp_f32_e32 v239, v239
	v_exp_f32_e32 v240, v240
	v_exp_f32_e32 v241, v241
	v_exp_f32_e32 v242, v242
	v_exp_f32_e32 v243, v243
	v_mov_b32_e32 v76, v124
	v_cndmask_b32_e64 v228, 0, v228, s[46:47]
	v_cndmask_b32_e64 v229, 0, v229, s[48:49]
	v_cndmask_b32_e64 v230, 0, v230, s[50:51]
	v_cndmask_b32_e64 v231, 0, v231, s[52:53]
	v_cndmask_b32_e64 v232, 0, v232, s[54:55]
	v_cndmask_b32_e64 v233, 0, v233, s[56:57]
	v_cndmask_b32_e64 v234, 0, v234, s[58:59]
	v_cndmask_b32_e64 v235, 0, v235, s[60:61]
	v_cndmask_b32_e64 v236, 0, v236, s[62:63]
	v_cndmask_b32_e64 v237, 0, v237, s[64:65]
	v_cndmask_b32_e64 v238, 0, v238, s[66:67]
	v_cndmask_b32_e64 v239, 0, v239, s[68:69]
	v_cndmask_b32_e64 v240, 0, v240, s[24:25]
	v_cndmask_b32_e64 v241, 0, v241, s[98:99]
	v_cndmask_b32_e64 v242, 0, v242, s[100:101]
	v_cndmask_b32_e64 v243, 0, v243, s[22:23]
	v_add_f32_e32 v120, v229, v228
	v_add_f32_e32 v120, v230, v120
	v_add_f32_e32 v120, v231, v120
	v_add_f32_e32 v120, v232, v120
	v_add_f32_e32 v120, v233, v120
	v_add_f32_e32 v120, v234, v120
	v_add_f32_e32 v120, v235, v120
	v_add_f32_e32 v120, v236, v120
	v_add_f32_e32 v120, v237, v120
	v_add_f32_e32 v120, v238, v120
	v_add_f32_e32 v120, v239, v120
	v_add_f32_e32 v120, v240, v120
	v_add_f32_e32 v120, v241, v120
	v_add_f32_e32 v120, v242, v120
	v_add_f32_e32 v120, v243, v120
	v_fmac_f32_e32 v120, v8, v126
	s_cmp_eq_u32 s72, 0
	v_mov_b32_e32 v8, v120
	s_cbranch_scc0 .Lc1_loop
	v_mov_b32_e32 v74, v170
	v_mov_b32_e32 v73, v177
	v_mov_b32_e32 v77, v171
	s_branch .LBB0_900

; __device__ __forceinline__ void nsa_wave(CArgs* Ap, int l, int b, int g, int tq0, const LAS float* lut, LAS float* imp, int lane) {
;     ...
;         for (; ns < nvalid; ++ns) { const int j0 = __builtin_amdgcn_readlane(selreg, ns), j1 = __builtin_amdgcn_readlane(selreg, 16 + ns), j2 = __builtin_amdgcn_readlane(selreg, 32 + ns), j3 = __builtin_amdgcn_readlane(selreg, 48 + ns);
;             if (!(j0 >= 0 && j0 == j1 && j0 == j2 && j0 == j3)) break; }
;         {
;             long kh[2][2], vh[4];
;             if (ns > 0) { const int j0_ = __builtin_amdgcn_readlane(selreg, 0); load_kh8(kh, Ks8 + (size_t)j0_ * 4096, 0, lane); load_vh8(vh, Vs8 + (size_t)j0_ * 4096, 0, lane); }
.LBB0_1242:
	s_or_b32 s0, s20, s17
	s_ashr_i32 s1, s0, 31
	s_lshl_b64 s[0:1], s[0:1], 19
	s_add_u32 s96, s87, s0
	s_addc_u32 s97, s88, s1
	s_add_u32 s0, s80, s0
	s_addc_u32 s1, s81, s1
	s_cmp_lg_u32 s24, 0
	s_cselect_b64 s[46:47], -1, 0
	s_cmp_eq_u32 s24, 0
	s_cbranch_scc1 .LBB0_1244
	v_readlane_b32 s48, v210, 0
	s_ashr_i32 s49, s48, 31
	s_lshl_b64 s[48:49], s[48:49], 12
	s_add_u32 s50, s96, s48
	s_addc_u32 s51, s97, s49
	s_add_u32 s48, s0, s48
	v_lshl_add_u64 v[8:9], s[50:51], 0, v[84:85]
	s_addc_u32 s49, s1, s49
	global_load_dwordx4 v[32:35], v[8:9], off
	global_load_dwordx4 v[36:39], v[8:9], off offset:1024
	v_lshl_add_u64 v[8:9], s[48:49], 0, v[84:85]
	global_load_dwordx4 v[40:43], v[8:9], off
	global_load_dwordx4 v[44:47], v[8:9], off offset:1024

; __device__ __forceinline__ void nsa_wave(CArgs* Ap, int l, int b, int g, int tq0, const LAS float* lut, LAS float* imp, int lane) {
;     ...
;             for (int hs = 0; hs < 2 * ns; ++hs) {
;                 const int s = hs >> 1, hh = hs & 1;
;                 const int j = __builtin_amdgcn_readlane(selreg, s);
;                 const bool more = hs + 1 < 2 * ns; const int s1 = (hs + 1) >> 1, h1 = (hs + 1) & 1;
;                 const int jn = more ? __builtin_amdgcn_readlane(selreg, s1) : 0;
;                 f32x4 acc[2];
;                 acc[0] = (f32x4){0.f, 0.f, 0.f, 0.f}; acc[1] = (f32x4){0.f, 0.f, 0.f, 0.f};
;                 qk_acch8(acc, kh, q8);
;                 if (more) load_kh8(kh, Ks8 + (size_t)jn * 4096, h1, lane);
.LBB0_1248:
	s_waitcnt vmcnt(3)
	v_mfma_f32_16x16x32_fp8_fp8 v[24:27], v[32:33], v[102:103], 0
	v_cndmask_b32_e64 v50, 0, 1, s[48:49]
	s_and_b32 s66, s65, 1
	v_cmp_ne_u32_e64 s[46:47], 1, v50
	s_nop 0
	v_mfma_f32_16x16x32_fp8_fp8 v[28:31], v[34:35], v[126:127], v[24:27]
	s_andn2_b64 vcc, exec, s[48:49]
	s_waitcnt vmcnt(2)
	v_mfma_f32_16x16x32_fp8_fp8 v[24:27], v[36:37], v[102:103], 0
	s_nop 0
	v_mfma_f32_16x16x32_fp8_fp8 v[24:27], v[38:39], v[126:127], v[24:27]
	s_cbranch_vccnz .LBB0_1250
	s_add_u32 s48, s96, s62
	s_addc_u32 s49, s97, s63
	v_lshl_or_b32 v228, s66, 11, v84
	global_load_dwordx4 v[32:35], v228, s[48:49]
	global_load_dwordx4 v[36:39], v228, s[48:49] offset:1024

; __device__ __forceinline__ void nsa_wave(CArgs* Ap, int l, int b, int g, int tq0, const LAS float* lut, LAS float* imp, int lane) {
;     ...
;                 if (__all(t - (j * 64 + 32 * hh + 31) >= 1023)) softmax_half_far(acc, lutg, st, Od);
;                 else { bf16x8 pB; softmax_half<1>(acc, j * 64 + 32 * hh, true, t, g4, lutg, st, Od, pB); }
;                 pv_acch8(Od, vh, p_to_fp8(acc));
;                 if (more) load_vh8(vh, Vs8 + (size_t)jn * 4096, h1, lane);
.LBB0_1254:
	v_mul_f32_e32 v25, 0x43800000, v50
	v_mul_f32_e32 v27, 0x43800000, v51
	v_mov_b32_e32 v26, 0
	v_mul_f32_e32 v30, 0x43800000, v54
	v_mul_f32_e32 v31, 0x43800000, v55
	v_cvt_pk_fp8_f32 v26, v25, v27
	v_mov_b32_e32 v27, 0
	v_cvt_pk_fp8_f32 v27, v30, v31
	v_sub_f32_e32 v24, v49, v144
	v_mul_f32_e32 v24, 0x3fb8aa3b, v24
	v_exp_f32_e32 v24, v24
	v_mul_f32_e32 v28, 0x43800000, v52
	v_mul_f32_e32 v29, 0x43800000, v53
	v_mul_f32_e32 v25, 0x43800000, v56
	v_mul_f32_e32 v30, 0x43800000, v57
	v_cvt_pk_fp8_f32 v26, v28, v29 op_sel:[0,0,1]
	v_cvt_pk_fp8_f32 v27, v25, v30 op_sel:[0,0,1]
	v_pk_mul_f32 v[22:23], v[22:23], v[24:25] op_sel_hi:[1,0]
	v_pk_mul_f32 v[20:21], v[20:21], v[24:25] op_sel_hi:[1,0]
	v_pk_mul_f32 v[18:19], v[18:19], v[24:25] op_sel_hi:[1,0]
	v_pk_mul_f32 v[16:17], v[16:17], v[24:25] op_sel_hi:[1,0]
	v_pk_mul_f32 v[14:15], v[14:15], v[24:25] op_sel_hi:[1,0]
	v_pk_mul_f32 v[12:13], v[12:13], v[24:25] op_sel_hi:[1,0]
	v_pk_mul_f32 v[10:11], v[10:11], v[24:25] op_sel_hi:[1,0]
	v_pk_mul_f32 v[8:9], v[8:9], v[24:25] op_sel_hi:[1,0]
	s_waitcnt vmcnt(1)
	v_mfma_f32_16x16x32_fp8_fp8 v[20:23], v[40:41], v[26:27], v[20:23]
	s_and_b64 vcc, exec, s[46:47]
	s_nop 0
	v_mfma_f32_16x16x32_fp8_fp8 v[16:19], v[42:43], v[26:27], v[16:19]
	s_waitcnt vmcnt(0)
	v_mfma_f32_16x16x32_fp8_fp8 v[12:15], v[44:45], v[26:27], v[12:15]
	s_nop 0
	v_mfma_f32_16x16x32_fp8_fp8 v[8:11], v[46:47], v[26:27], v[8:11]
	s_cbranch_vccnz .LBB0_1256
	s_add_u32 s46, s0, s62
	s_addc_u32 s47, s1, s63
	v_lshl_or_b32 v25, s66, 11, v84
	global_load_dwordx4 v[40:43], v25, s[46:47]
	global_load_dwordx4 v[44:47], v25, s[46:47] offset:1024

; __device__ __forceinline__ void nsa_wave(CArgs* Ap, int l, int b, int g, int tq0, const LAS float* lut, LAS float* imp, int lane) {
;     ...
;         const int nh = 2 * nvalid, h0 = 2 * ns;
;         long kq[4][2][2], vq[4][4];
;         if (h0 < nh) {
; #pragma unroll
;             for (int q2 = 0; q2 < 4; ++q2) { int j = __builtin_amdgcn_readlane(selreg, 16 * q2 + ns); j = j < 0 ? 0 : j; load_kh8(kq[q2], Ks8 + (size_t)j * 4096, 0, lane); load_vh8(vq[q2], Vs8 + (size_t)j * 4096, 0, lane); } }
;         for (int hs = h0; hs < nh; ++hs) {
;             const int s = hs >> 1, hh = hs & 1;
;             const int jm = __shfl(selreg, 16 * qi + s);
;             f32x4 acc[2];
;             acc[0] = (f32x4){0.f, 0.f, 0.f, 0.f}; acc[1] = (f32x4){0.f, 0.f, 0.f, 0.f};
; #pragma unroll
;             for (int q2 = 0; q2 < 4; ++q2) { long qm[2]; qm[0] = (qi == q2) ? q8[0] : 0l; qm[1] = (qi == q2) ? q8[1] : 0l; qk_acch8(acc, kq[q2], qm); }
.LBB0_1259:
	s_lshl_b32 s22, s22, 1
	s_cmp_gt_i32 s23, s22
	s_cbranch_scc1 .LBB0_1279
	v_readlane_b32 s25, v210, s24
	s_max_i32 s72, s25, 0
	s_lshl_b64 s[50:51], s[72:73], 12
	s_add_u32 s48, s96, s50
	s_addc_u32 s49, s97, s51
	global_load_dwordx4 v[32:35], v84, s[48:49]
	global_load_dwordx4 v[36:39], v84, s[48:49] offset:1024
	s_add_i32 s25, s24, 16
	v_readlane_b32 s25, v210, s25
	s_max_i32 s72, s25, 0
	s_lshl_b64 s[52:53], s[72:73], 12
	s_add_u32 s48, s96, s52
	s_addc_u32 s49, s97, s53
	global_load_dwordx4 v[48:51], v84, s[48:49]
	global_load_dwordx4 v[52:55], v84, s[48:49] offset:1024
	s_xor_b32 s25, s24, 32
	v_readlane_b32 s25, v210, s25
	s_max_i32 s72, s25, 0
	s_lshl_b64 s[54:55], s[72:73], 12
	s_add_u32 s48, s96, s54
	s_addc_u32 s49, s97, s55
	global_load_dwordx4 v[64:67], v84, s[48:49]
	global_load_dwordx4 v[68:71], v84, s[48:49] offset:1024
	s_add_i32 s25, s24, 48
	v_readlane_b32 s25, v210, s25
	s_max_i32 s72, s25, 0
	s_lshl_b64 s[56:57], s[72:73], 12
	s_add_u32 s48, s96, s56
	s_addc_u32 s49, s97, s57
	global_load_dwordx4 v[112:115], v84, s[48:49]
	global_load_dwordx4 v[116:119], v84, s[48:49] offset:1024
	s_add_u32 s48, s0, s50
	s_addc_u32 s49, s1, s51
	global_load_dwordx4 v[40:43], v84, s[48:49]
	global_load_dwordx4 v[44:47], v84, s[48:49] offset:1024
	s_add_u32 s48, s0, s52
	s_addc_u32 s49, s1, s53
	global_load_dwordx4 v[56:59], v84, s[48:49]
	global_load_dwordx4 v[60:63], v84, s[48:49] offset:1024
	s_add_u32 s48, s0, s54
	s_addc_u32 s49, s1, s55
	global_load_dwordx4 v[74:77], v84, s[48:49]
	global_load_dwordx4 v[78:81], v84, s[48:49] offset:1024
	s_add_u32 s48, s0, s56
	s_addc_u32 s49, s1, s57
	global_load_dwordx4 v[106:109], v84, s[48:49]
	global_load_dwordx4 v[122:125], v84, s[48:49] offset:1024
	v_cndmask_b32_e64 v83, 0, v103, s[6:7]
	v_cndmask_b32_e64 v82, 0, v102, s[6:7]
	v_cndmask_b32_e64 v99, 0, v103, s[8:9]
	v_cndmask_b32_e64 v98, 0, v102, s[8:9]
	v_cndmask_b32_e64 v101, 0, v103, s[10:11]
	v_cndmask_b32_e64 v100, 0, v102, s[10:11]
	v_cndmask_b32_e64 v103, 0, v103, s[12:13]
	v_cndmask_b32_e64 v102, 0, v102, s[12:13]
	v_cndmask_b32_e64 v105, 0, v127, s[6:7]
	v_cndmask_b32_e64 v104, 0, v126, s[6:7]
	v_cndmask_b32_e64 v111, 0, v127, s[8:9]
	v_cndmask_b32_e64 v110, 0, v126, s[8:9]
	v_cndmask_b32_e64 v121, 0, v127, s[10:11]
	v_cndmask_b32_e64 v120, 0, v126, s[10:11]
	v_cndmask_b32_e64 v127, 0, v127, s[12:13]
	v_cndmask_b32_e64 v126, 0, v126, s[12:13]
	s_lshl_b32 s24, s24, 6

; __device__ __forceinline__ void nsa_wave(CArgs* Ap, int l, int b, int g, int tq0, const LAS float* lut, LAS float* imp, int lane) {
;     ...
;         for (int hs = h0; hs < nh; ++hs) {
;             const int s = hs >> 1, hh = hs & 1;
;             const int jm = __shfl(selreg, 16 * qi + s);
;             f32x4 acc[2];
;             acc[0] = (f32x4){0.f, 0.f, 0.f, 0.f}; acc[1] = (f32x4){0.f, 0.f, 0.f, 0.f};
; #pragma unroll
;             for (int q2 = 0; q2 < 4; ++q2) { long qm[2]; qm[0] = (qi == q2) ? q8[0] : 0l; qm[1] = (qi == q2) ? q8[1] : 0l; qk_acch8(acc, kq[q2], qm); }
;             const bool more = hs + 1 < nh; const int s1 = (hs + 1) >> 1, h1 = (hs + 1) & 1;
;             int jn[4];
; #pragma unroll
;             for (int q2 = 0; q2 < 4; ++q2) { int j = more ? __builtin_amdgcn_readlane(selreg, 16 * q2 + s1) : 0; jn[q2] = j < 0 ? 0 : j; }
;             if (more) {
; #pragma unroll
;                 for (int q2 = 0; q2 < 4; ++q2) load_kh8(kq[q2], Ks8 + (size_t)jn[q2] * 4096, h1, lane); }
.LBB0_1269:
	s_waitcnt vmcnt(15)
	v_mfma_f32_16x16x32_fp8_fp8 v[24:27], v[32:33], v[82:83], 0
	s_lshr_b32 s23, s23, 1
	v_add_u32_e32 v150, s23, v201
	v_and_or_b32 v150, v150, 63, v73
	s_waitcnt vmcnt(14)
	v_mfma_f32_16x16x32_fp8_fp8 v[28:31], v[36:37], v[82:83], 0
	v_lshlrev_b32_e32 v150, 2, v150
	ds_bpermute_b32 v214, v150, v210
	s_and_b32 s23, s25, 1
	v_mfma_f32_16x16x32_fp8_fp8 v[24:27], v[34:35], v[104:105], v[24:27]
	s_and_b64 vcc, exec, s[48:49]
	s_nop 0
	v_mfma_f32_16x16x32_fp8_fp8 v[28:31], v[38:39], v[104:105], v[28:31]
	s_waitcnt vmcnt(13)
	v_mfma_f32_16x16x32_fp8_fp8 v[24:27], v[48:49], v[98:99], v[24:27]
	s_waitcnt vmcnt(12)
	v_mfma_f32_16x16x32_fp8_fp8 v[28:31], v[52:53], v[98:99], v[28:31]
	v_mfma_f32_16x16x32_fp8_fp8 v[24:27], v[50:51], v[110:111], v[24:27]
	s_nop 0
	v_mfma_f32_16x16x32_fp8_fp8 v[28:31], v[54:55], v[110:111], v[28:31]
	s_waitcnt vmcnt(11)
	v_mfma_f32_16x16x32_fp8_fp8 v[24:27], v[64:65], v[100:101], v[24:27]
	s_waitcnt vmcnt(10)
	v_mfma_f32_16x16x32_fp8_fp8 v[28:31], v[68:69], v[100:101], v[28:31]
	v_mfma_f32_16x16x32_fp8_fp8 v[24:27], v[66:67], v[120:121], v[24:27]
	s_nop 0
	v_mfma_f32_16x16x32_fp8_fp8 v[28:31], v[70:71], v[120:121], v[28:31]
	s_waitcnt vmcnt(9)
	v_mfma_f32_16x16x32_fp8_fp8 v[24:27], v[112:113], v[102:103], v[24:27]
	s_waitcnt vmcnt(8)
	v_mfma_f32_16x16x32_fp8_fp8 v[28:31], v[116:117], v[102:103], v[28:31]
	v_mfma_f32_16x16x32_fp8_fp8 v[24:27], v[114:115], v[126:127], v[24:27]
	s_nop 0
	v_mfma_f32_16x16x32_fp8_fp8 v[28:31], v[118:119], v[126:127], v[28:31]
	s_cbranch_vccz .LBB0_1271
	v_lshl_or_b32 v228, s23, 11, v84
	s_add_u32 s48, s96, s66
	s_addc_u32 s49, s97, s67
	global_load_dwordx4 v[32:35], v228, s[48:49]
	global_load_dwordx4 v[36:39], v228, s[48:49] offset:1024
	s_add_u32 s48, s96, s64
	s_addc_u32 s49, s97, s65
	global_load_dwordx4 v[48:51], v228, s[48:49]
	global_load_dwordx4 v[52:55], v228, s[48:49] offset:1024
	s_add_u32 s48, s96, s76
	s_addc_u32 s49, s97, s77
	global_load_dwordx4 v[64:67], v228, s[48:49]
	global_load_dwordx4 v[68:71], v228, s[48:49] offset:1024
	s_add_u32 s48, s96, s68
	s_addc_u32 s49, s97, s69
	global_load_dwordx4 v[112:115], v228, s[48:49]
	global_load_dwordx4 v[116:119], v228, s[48:49] offset:1024

; __device__ __forceinline__ void nsa_wave(CArgs* Ap, int l, int b, int g, int tq0, const LAS float* lut, LAS float* imp, int lane) {
;     ...
;             if (__all(jm >= 0 && t - (jm * 64 + 32 * hh + 31) >= 1023)) softmax_half_far(acc, lutg, st, Od);
;             else { bf16x8 pB; softmax_half<1>(acc, (jm < 0 ? 0 : jm) * 64 + 32 * hh, jm >= 0, t, g4, lutg, st, Od, pB); }
;             const long p8 = p_to_fp8(acc);
; #pragma unroll
;             for (int q2 = 0; q2 < 4; ++q2) { const long pm = (qi == q2) ? p8 : 0l; pv_acch8(Od, vq[q2], pm); }
;             if (more) {
; #pragma unroll
;                 for (int q2 = 0; q2 < 4; ++q2) load_vh8(vq[q2], Vs8 + (size_t)jn[q2] * 4096, h1, lane); }
.LBB0_1275:
	v_sub_f32_e32 v24, v144, v213
	v_mul_f32_e32 v25, 0x43800000, v216
	v_mul_f32_e32 v26, 0x43800000, v217
	v_mul_f32_e32 v29, 0x43800000, v220
	v_mul_f32_e32 v30, 0x43800000, v221
	v_mov_b32_e32 v31, 0
	v_mov_b32_e32 v144, 0
	v_cvt_pk_fp8_f32 v144, v29, v30
	v_cvt_pk_fp8_f32 v31, v25, v26
	v_mul_f32_e32 v24, 0x3fb8aa3b, v24
	v_mul_f32_e32 v27, 0x43800000, v218
	v_mul_f32_e32 v28, 0x43800000, v219
	v_mul_f32_e32 v25, 0x43800000, v222
	v_mul_f32_e32 v26, 0x43800000, v223
	v_exp_f32_e32 v24, v24
	v_cvt_pk_fp8_f32 v144, v25, v26 op_sel:[0,0,1]
	v_cvt_pk_fp8_f32 v31, v27, v28 op_sel:[0,0,1]
	s_and_b64 vcc, exec, s[46:47]
	v_pk_mul_f32 v[22:23], v[22:23], v[24:25] op_sel_hi:[1,0]
	v_pk_mul_f32 v[20:21], v[20:21], v[24:25] op_sel_hi:[1,0]
	v_cndmask_b32_e64 v27, 0, v144, s[6:7]
	v_cndmask_b32_e64 v26, 0, v31, s[6:7]
	v_pk_mul_f32 v[18:19], v[18:19], v[24:25] op_sel_hi:[1,0]
	v_pk_mul_f32 v[16:17], v[16:17], v[24:25] op_sel_hi:[1,0]
	v_pk_mul_f32 v[14:15], v[14:15], v[24:25] op_sel_hi:[1,0]
	v_pk_mul_f32 v[12:13], v[12:13], v[24:25] op_sel_hi:[1,0]
	v_pk_mul_f32 v[10:11], v[10:11], v[24:25] op_sel_hi:[1,0]
	v_pk_mul_f32 v[8:9], v[8:9], v[24:25] op_sel_hi:[1,0]
	s_waitcnt vmcnt(7)
	s_nop 0
	v_mfma_f32_16x16x32_fp8_fp8 v[20:23], v[40:41], v[26:27], v[20:23]
	v_mfma_f32_16x16x32_fp8_fp8 v[16:19], v[42:43], v[26:27], v[16:19]
	s_waitcnt vmcnt(6)
	v_mfma_f32_16x16x32_fp8_fp8 v[12:15], v[44:45], v[26:27], v[12:15]
	v_mfma_f32_16x16x32_fp8_fp8 v[8:11], v[46:47], v[26:27], v[8:11]
	v_cndmask_b32_e64 v27, 0, v144, s[8:9]
	v_cndmask_b32_e64 v26, 0, v31, s[8:9]
	s_waitcnt vmcnt(5)
	s_nop 0
	v_mfma_f32_16x16x32_fp8_fp8 v[20:23], v[56:57], v[26:27], v[20:23]
	v_mfma_f32_16x16x32_fp8_fp8 v[16:19], v[58:59], v[26:27], v[16:19]
	s_waitcnt vmcnt(4)
	v_mfma_f32_16x16x32_fp8_fp8 v[12:15], v[60:61], v[26:27], v[12:15]
	v_mfma_f32_16x16x32_fp8_fp8 v[8:11], v[62:63], v[26:27], v[8:11]
	v_cndmask_b32_e64 v27, 0, v144, s[10:11]
	v_cndmask_b32_e64 v26, 0, v31, s[10:11]
	s_waitcnt vmcnt(3)
	s_nop 0
	v_mfma_f32_16x16x32_fp8_fp8 v[20:23], v[74:75], v[26:27], v[20:23]
	v_mfma_f32_16x16x32_fp8_fp8 v[16:19], v[76:77], v[26:27], v[16:19]
	s_waitcnt vmcnt(2)
	v_mfma_f32_16x16x32_fp8_fp8 v[12:15], v[78:79], v[26:27], v[12:15]
	v_mfma_f32_16x16x32_fp8_fp8 v[8:11], v[80:81], v[26:27], v[8:11]
	v_cndmask_b32_e64 v27, 0, v144, s[12:13]
	v_cndmask_b32_e64 v26, 0, v31, s[12:13]
	s_waitcnt vmcnt(1)
	s_nop 0
	v_mfma_f32_16x16x32_fp8_fp8 v[20:23], v[106:107], v[26:27], v[20:23]
	v_mfma_f32_16x16x32_fp8_fp8 v[16:19], v[108:109], v[26:27], v[16:19]
	s_waitcnt vmcnt(0)
	v_mfma_f32_16x16x32_fp8_fp8 v[12:15], v[122:123], v[26:27], v[12:15]
	v_mfma_f32_16x16x32_fp8_fp8 v[8:11], v[124:125], v[26:27], v[8:11]
	s_cbranch_vccnz .LBB0_1277
	v_lshl_or_b32 v144, s23, 11, v84
	s_add_u32 s48, s0, s66
	s_addc_u32 s49, s1, s67
	global_load_dwordx4 v[40:43], v144, s[48:49]
	global_load_dwordx4 v[44:47], v144, s[48:49] offset:1024
	s_add_u32 s48, s0, s64
	s_addc_u32 s49, s1, s65
	global_load_dwordx4 v[56:59], v144, s[48:49]
	global_load_dwordx4 v[60:63], v144, s[48:49] offset:1024
	s_add_u32 s48, s0, s76
	s_addc_u32 s49, s1, s77
	global_load_dwordx4 v[74:77], v144, s[48:49]
	global_load_dwordx4 v[78:81], v144, s[48:49] offset:1024
	s_add_u32 s48, s0, s68
	s_addc_u32 s49, s1, s69
	global_load_dwordx4 v[106:109], v144, s[48:49]
	global_load_dwordx4 v[122:125], v144, s[48:49] offset:1024
